# 256sq GEMM loops: per-cluster s_setprio flips deleted, one static s_setprio 1 for waves 4-7 per phase
# baseline (speedup 1.0000x reference)
.LBB0_19:
	s_setprio 0
	v_readlane_b32 s36, v255, 31
	s_add_i32 s74, s74, 1
	v_readlane_b32 s37, v255, 32
	s_cmp_ge_i32 s74, s37
	v_readlane_b32 s56, v255, 33
	s_cbranch_scc0 .LBB0_20
	s_getpc_b64 s[98:99]

.LBB0_151:
	v_readfirstlane_b32 s98, v228
	s_nop 3
	s_cmp_ge_u32 s98, 0x100
	s_cbranch_scc0 .Lprio_done_158
	s_setprio 1

.LBB0_158:
	s_add_u32 s42, s46, 0xfffc0080
	s_addc_u32 s43, s47, -1
	s_add_i32 m0, s53, 0xc000
	s_cmp_eq_u32 vcc_hi, 12
	s_cselect_b32 s51, s3, s43
	s_cselect_b32 s50, s94, s42
	ds_read_b128 v[64:67], v159 offset:0
	ds_read_b128 v[68:71], v159 offset:1024
	ds_read_b128 v[72:75], v159 offset:2048
	ds_read_b128 v[76:79], v159 offset:3072
	v_lshl_add_u64 v[168:169], s[46:47], 0, v[150:151]
	ds_read_b128 v[174:177], v157 offset:0
	ds_read_b128 v[178:181], v157 offset:1024
	ds_read_b128 v[182:185], v157 offset:2048
	ds_read_b128 v[186:189], v157 offset:3072
	ds_read_b128 v[190:193], v157 offset:4096
	ds_read_b128 v[194:197], v157 offset:5120
	ds_read_b128 v[210:213], v157 offset:6144
	ds_read_b128 v[214:217], v157 offset:7168
	global_load_lds_dwordx4 v[168:169], off
	v_lshl_add_u64 v[168:169], s[46:47], 0, v[152:153]
	s_mov_b32 m0, s72
	s_cselect_b32 s49, s1, vcc_lo
	global_load_lds_dwordx4 v[168:169], off
	s_waitcnt lgkmcnt(8)
	s_barrier
	s_waitcnt lgkmcnt(0)
	s_waitcnt lgkmcnt(0)
	s_cselect_b32 s48, s96, s97
	v_mfma_f32_16x16x32_bf16 v[140:143], v[64:67], v[174:177], v[140:143]
	v_mfma_f32_16x16x32_bf16 v[136:139], v[72:75], v[174:177], v[136:139]
	v_mfma_f32_16x16x32_bf16 v[124:127], v[64:67], v[182:185], v[124:127]
	v_mfma_f32_16x16x32_bf16 v[120:123], v[72:75], v[182:185], v[120:123]
	v_mfma_f32_16x16x32_bf16 v[108:111], v[64:67], v[190:193], v[108:111]
	v_mfma_f32_16x16x32_bf16 v[104:107], v[72:75], v[190:193], v[104:107]
	v_mfma_f32_16x16x32_bf16 v[92:95], v[64:67], v[210:213], v[92:95]
	v_mfma_f32_16x16x32_bf16 v[88:91], v[72:75], v[210:213], v[88:91]
	v_mfma_f32_16x16x32_bf16 v[140:143], v[68:71], v[178:181], v[140:143]
	v_mfma_f32_16x16x32_bf16 v[136:139], v[76:79], v[178:181], v[136:139]
	v_mfma_f32_16x16x32_bf16 v[124:127], v[68:71], v[186:189], v[124:127]
	v_mfma_f32_16x16x32_bf16 v[120:123], v[76:79], v[186:189], v[120:123]
	v_mfma_f32_16x16x32_bf16 v[108:111], v[68:71], v[194:197], v[108:111]
	v_mfma_f32_16x16x32_bf16 v[104:107], v[76:79], v[194:197], v[104:107]
	v_mfma_f32_16x16x32_bf16 v[92:95], v[68:71], v[214:217], v[92:95]
	v_mfma_f32_16x16x32_bf16 v[88:91], v[76:79], v[214:217], v[88:91]
	s_barrier
	s_mov_b32 m0, s45
	v_lshl_add_u64 v[168:169], s[48:49], 0, v[200:201]
	ds_read_b128 v[218:221], v161 offset:0
	ds_read_b128 v[222:225], v161 offset:1024
	ds_read_b128 v[230:233], v161 offset:2048
	ds_read_b128 v[248:251], v161 offset:3072
	global_load_lds_dwordx4 v[168:169], off
	v_lshl_add_u64 v[198:199], s[48:49], 0, v[144:145]
	s_mov_b32 m0, s56
	s_nop 0
	global_load_lds_dwordx4 v[198:199], off
	s_barrier
	s_waitcnt lgkmcnt(0)
	v_mfma_f32_16x16x32_bf16 v[132:135], v[218:221], v[174:177], v[132:135]
	v_mfma_f32_16x16x32_bf16 v[128:131], v[230:233], v[174:177], v[128:131]
	v_mfma_f32_16x16x32_bf16 v[116:119], v[218:221], v[182:185], v[116:119]
	v_mfma_f32_16x16x32_bf16 v[112:115], v[230:233], v[182:185], v[112:115]
	v_mfma_f32_16x16x32_bf16 v[100:103], v[218:221], v[190:193], v[100:103]
	v_mfma_f32_16x16x32_bf16 v[96:99], v[230:233], v[190:193], v[96:99]
	v_mfma_f32_16x16x32_bf16 v[84:87], v[218:221], v[210:213], v[84:87]
	v_mfma_f32_16x16x32_bf16 v[80:83], v[230:233], v[210:213], v[80:83]
	v_mfma_f32_16x16x32_bf16 v[132:135], v[222:225], v[178:181], v[132:135]
	v_mfma_f32_16x16x32_bf16 v[128:131], v[248:251], v[178:181], v[128:131]
	v_mfma_f32_16x16x32_bf16 v[116:119], v[222:225], v[186:189], v[116:119]
	v_mfma_f32_16x16x32_bf16 v[112:115], v[248:251], v[186:189], v[112:115]
	v_mfma_f32_16x16x32_bf16 v[100:103], v[222:225], v[194:197], v[100:103]
	v_mfma_f32_16x16x32_bf16 v[96:99], v[248:251], v[194:197], v[96:99]
	v_mfma_f32_16x16x32_bf16 v[84:87], v[222:225], v[214:217], v[84:87]
	v_mfma_f32_16x16x32_bf16 v[80:83], v[248:251], v[214:217], v[80:83]
	s_mov_b32 m0, s53
	v_lshl_add_u64 v[226:227], s[50:51], 0, v[148:149]
	s_barrier
	ds_read_b128 v[174:177], v163 offset:0
	ds_read_b128 v[178:181], v163 offset:1024
	ds_read_b128 v[182:185], v163 offset:2048
	ds_read_b128 v[186:189], v163 offset:3072
	ds_read_b128 v[190:193], v163 offset:4096
	ds_read_b128 v[194:197], v163 offset:5120
	ds_read_b128 v[210:213], v163 offset:6144
	ds_read_b128 v[214:217], v163 offset:7168
	global_load_lds_dwordx4 v[226:227], off
	v_lshl_add_u64 v[208:209], s[50:51], 0, v[146:147]
	s_mov_b32 m0, s57
	s_nop 0
	global_load_lds_dwordx4 v[208:209], off
	s_barrier
	s_waitcnt lgkmcnt(0)
	v_mfma_f32_16x16x32_bf16 v[60:63], v[64:67], v[174:177], v[60:63]
	v_mfma_f32_16x16x32_bf16 v[56:59], v[72:75], v[174:177], v[56:59]
	v_mfma_f32_16x16x32_bf16 v[44:47], v[64:67], v[182:185], v[44:47]
	v_mfma_f32_16x16x32_bf16 v[40:43], v[72:75], v[182:185], v[40:43]
	v_mfma_f32_16x16x32_bf16 v[28:31], v[64:67], v[190:193], v[28:31]
	v_mfma_f32_16x16x32_bf16 v[24:27], v[72:75], v[190:193], v[24:27]
	v_mfma_f32_16x16x32_bf16 v[12:15], v[64:67], v[210:213], v[12:15]
	v_mfma_f32_16x16x32_bf16 v[8:11], v[72:75], v[210:213], v[8:11]
	v_mfma_f32_16x16x32_bf16 v[60:63], v[68:71], v[178:181], v[60:63]
	v_mfma_f32_16x16x32_bf16 v[56:59], v[76:79], v[178:181], v[56:59]
	v_mfma_f32_16x16x32_bf16 v[44:47], v[68:71], v[186:189], v[44:47]
	v_mfma_f32_16x16x32_bf16 v[40:43], v[76:79], v[186:189], v[40:43]
	v_mfma_f32_16x16x32_bf16 v[28:31], v[68:71], v[194:197], v[28:31]
	v_mfma_f32_16x16x32_bf16 v[24:27], v[76:79], v[194:197], v[24:27]
	v_mfma_f32_16x16x32_bf16 v[12:15], v[68:71], v[214:217], v[12:15]
	v_mfma_f32_16x16x32_bf16 v[8:11], v[76:79], v[214:217], v[8:11]
	s_barrier
	s_add_u32 s42, s48, 0x40000
	s_addc_u32 s43, s49, 0
	s_mov_b32 m0, s58
	v_lshl_add_u64 v[64:65], s[42:43], 0, v[200:201]
	global_load_lds_dwordx4 v[64:65], off
	v_lshl_add_u64 v[64:65], s[42:43], 0, v[144:145]
	s_mov_b32 m0, s59
	s_nop 0
	global_load_lds_dwordx4 v[64:65], off
	s_waitcnt vmcnt(6)
	s_barrier
	v_mfma_f32_16x16x32_bf16 v[52:55], v[218:221], v[174:177], v[52:55]
	v_mfma_f32_16x16x32_bf16 v[48:51], v[230:233], v[174:177], v[48:51]
	v_mfma_f32_16x16x32_bf16 v[36:39], v[218:221], v[182:185], v[36:39]
	v_mfma_f32_16x16x32_bf16 v[32:35], v[230:233], v[182:185], v[32:35]
	v_mfma_f32_16x16x32_bf16 v[20:23], v[218:221], v[190:193], v[20:23]
	v_mfma_f32_16x16x32_bf16 v[16:19], v[230:233], v[190:193], v[16:19]
	v_mfma_f32_16x16x32_bf16 v[4:7], v[218:221], v[210:213], v[4:7]
	v_mfma_f32_16x16x32_bf16 v[0:3], v[230:233], v[210:213], v[0:3]
	v_mfma_f32_16x16x32_bf16 v[52:55], v[222:225], v[178:181], v[52:55]
	v_mfma_f32_16x16x32_bf16 v[48:51], v[248:251], v[178:181], v[48:51]
	v_mfma_f32_16x16x32_bf16 v[36:39], v[222:225], v[186:189], v[36:39]
	v_mfma_f32_16x16x32_bf16 v[32:35], v[248:251], v[186:189], v[32:35]
	v_mfma_f32_16x16x32_bf16 v[20:23], v[222:225], v[194:197], v[20:23]
	v_mfma_f32_16x16x32_bf16 v[16:19], v[248:251], v[194:197], v[16:19]
	v_mfma_f32_16x16x32_bf16 v[4:7], v[222:225], v[214:217], v[4:7]
	v_mfma_f32_16x16x32_bf16 v[0:3], v[248:251], v[214:217], v[0:3]
	s_barrier
	ds_read_b128 v[64:67], v165 offset:0
	ds_read_b128 v[68:71], v165 offset:1024
	ds_read_b128 v[72:75], v165 offset:2048
	ds_read_b128 v[76:79], v165 offset:3072
	s_add_u32 s42, s50, 0x40000
	s_addc_u32 s43, s51, 0
	s_mov_b32 m0, s60
	v_lshl_add_u64 v[218:219], s[42:43], 0, v[148:149]
	ds_read_b128 v[174:177], v167 offset:0
	ds_read_b128 v[178:181], v167 offset:1024
	ds_read_b128 v[182:185], v167 offset:2048
	ds_read_b128 v[186:189], v167 offset:3072
	ds_read_b128 v[190:193], v167 offset:4096
	ds_read_b128 v[194:197], v167 offset:5120
	ds_read_b128 v[210:213], v167 offset:6144
	ds_read_b128 v[214:217], v167 offset:7168
	global_load_lds_dwordx4 v[218:219], off
	v_lshl_add_u64 v[218:219], s[42:43], 0, v[146:147]
	s_mov_b32 m0, s61
	s_nop 0
	global_load_lds_dwordx4 v[218:219], off
	s_waitcnt lgkmcnt(8)
	s_barrier
	s_waitcnt lgkmcnt(0)
	s_waitcnt lgkmcnt(0)
	v_mfma_f32_16x16x32_bf16 v[140:143], v[64:67], v[174:177], v[140:143]
	v_mfma_f32_16x16x32_bf16 v[136:139], v[72:75], v[174:177], v[136:139]
	v_mfma_f32_16x16x32_bf16 v[124:127], v[64:67], v[182:185], v[124:127]
	v_mfma_f32_16x16x32_bf16 v[120:123], v[72:75], v[182:185], v[120:123]
	v_mfma_f32_16x16x32_bf16 v[108:111], v[64:67], v[190:193], v[108:111]
	v_mfma_f32_16x16x32_bf16 v[104:107], v[72:75], v[190:193], v[104:107]
	v_mfma_f32_16x16x32_bf16 v[92:95], v[64:67], v[210:213], v[92:95]
	v_mfma_f32_16x16x32_bf16 v[88:91], v[72:75], v[210:213], v[88:91]
	v_mfma_f32_16x16x32_bf16 v[140:143], v[68:71], v[178:181], v[140:143]
	v_mfma_f32_16x16x32_bf16 v[136:139], v[76:79], v[178:181], v[136:139]
	v_mfma_f32_16x16x32_bf16 v[124:127], v[68:71], v[186:189], v[124:127]
	v_mfma_f32_16x16x32_bf16 v[120:123], v[76:79], v[186:189], v[120:123]
	v_mfma_f32_16x16x32_bf16 v[108:111], v[68:71], v[194:197], v[108:111]
	v_mfma_f32_16x16x32_bf16 v[104:107], v[76:79], v[194:197], v[104:107]
	v_mfma_f32_16x16x32_bf16 v[92:95], v[68:71], v[214:217], v[92:95]
	v_mfma_f32_16x16x32_bf16 v[88:91], v[76:79], v[214:217], v[88:91]
	s_barrier
	s_mov_b32 m0, s62
	v_lshl_add_u64 v[168:169], v[168:169], 0, s[34:35]
	ds_read_b128 v[218:221], v170 offset:0
	ds_read_b128 v[222:225], v170 offset:1024
	ds_read_b128 v[230:233], v170 offset:2048
	ds_read_b128 v[248:251], v170 offset:3072
	global_load_lds_dwordx4 v[168:169], off
	v_lshl_add_u64 v[168:169], v[198:199], 0, s[34:35]
	s_mov_b32 m0, s63
	s_nop 0
	global_load_lds_dwordx4 v[168:169], off
	s_barrier
	s_waitcnt lgkmcnt(0)
	v_mfma_f32_16x16x32_bf16 v[132:135], v[218:221], v[174:177], v[132:135]
	v_mfma_f32_16x16x32_bf16 v[128:131], v[230:233], v[174:177], v[128:131]
	v_mfma_f32_16x16x32_bf16 v[116:119], v[218:221], v[182:185], v[116:119]
	v_mfma_f32_16x16x32_bf16 v[112:115], v[230:233], v[182:185], v[112:115]
	v_mfma_f32_16x16x32_bf16 v[100:103], v[218:221], v[190:193], v[100:103]
	v_mfma_f32_16x16x32_bf16 v[96:99], v[230:233], v[190:193], v[96:99]
	v_mfma_f32_16x16x32_bf16 v[84:87], v[218:221], v[210:213], v[84:87]
	v_mfma_f32_16x16x32_bf16 v[80:83], v[230:233], v[210:213], v[80:83]
	v_mfma_f32_16x16x32_bf16 v[132:135], v[222:225], v[178:181], v[132:135]
	v_mfma_f32_16x16x32_bf16 v[128:131], v[248:251], v[178:181], v[128:131]
	v_mfma_f32_16x16x32_bf16 v[116:119], v[222:225], v[186:189], v[116:119]
	v_mfma_f32_16x16x32_bf16 v[112:115], v[248:251], v[186:189], v[112:115]
	v_mfma_f32_16x16x32_bf16 v[100:103], v[222:225], v[194:197], v[100:103]
	v_mfma_f32_16x16x32_bf16 v[96:99], v[248:251], v[194:197], v[96:99]
	v_mfma_f32_16x16x32_bf16 v[84:87], v[222:225], v[214:217], v[84:87]
	v_mfma_f32_16x16x32_bf16 v[80:83], v[248:251], v[214:217], v[80:83]
	s_mov_b32 m0, s64
	v_lshl_add_u64 v[168:169], v[226:227], 0, s[34:35]
	s_barrier
	ds_read_b128 v[174:177], v171 offset:0
	ds_read_b128 v[178:181], v171 offset:1024
	ds_read_b128 v[182:185], v171 offset:2048
	ds_read_b128 v[186:189], v171 offset:3072
	ds_read_b128 v[190:193], v171 offset:4096
	ds_read_b128 v[194:197], v171 offset:5120
	ds_read_b128 v[210:213], v171 offset:6144
	ds_read_b128 v[214:217], v171 offset:7168
	global_load_lds_dwordx4 v[168:169], off
	v_lshl_add_u64 v[168:169], v[208:209], 0, s[34:35]
	s_mov_b32 m0, s65
	s_nop 0
	global_load_lds_dwordx4 v[168:169], off
	s_barrier
	s_waitcnt lgkmcnt(0)
	v_mfma_f32_16x16x32_bf16 v[60:63], v[64:67], v[174:177], v[60:63]
	v_mfma_f32_16x16x32_bf16 v[56:59], v[72:75], v[174:177], v[56:59]
	v_mfma_f32_16x16x32_bf16 v[44:47], v[64:67], v[182:185], v[44:47]
	v_mfma_f32_16x16x32_bf16 v[40:43], v[72:75], v[182:185], v[40:43]
	v_mfma_f32_16x16x32_bf16 v[28:31], v[64:67], v[190:193], v[28:31]
	v_mfma_f32_16x16x32_bf16 v[24:27], v[72:75], v[190:193], v[24:27]
	v_mfma_f32_16x16x32_bf16 v[12:15], v[64:67], v[210:213], v[12:15]
	v_mfma_f32_16x16x32_bf16 v[8:11], v[72:75], v[210:213], v[8:11]
	v_mfma_f32_16x16x32_bf16 v[60:63], v[68:71], v[178:181], v[60:63]
	v_mfma_f32_16x16x32_bf16 v[56:59], v[76:79], v[178:181], v[56:59]
	v_mfma_f32_16x16x32_bf16 v[44:47], v[68:71], v[186:189], v[44:47]
	v_mfma_f32_16x16x32_bf16 v[40:43], v[76:79], v[186:189], v[40:43]
	v_mfma_f32_16x16x32_bf16 v[28:31], v[68:71], v[194:197], v[28:31]
	v_mfma_f32_16x16x32_bf16 v[24:27], v[76:79], v[194:197], v[24:27]
	v_mfma_f32_16x16x32_bf16 v[12:15], v[68:71], v[214:217], v[12:15]
	v_mfma_f32_16x16x32_bf16 v[8:11], v[76:79], v[214:217], v[8:11]
	s_barrier
	s_add_u32 s42, s48, 0x40080
	s_addc_u32 s43, s49, 0
	s_mov_b32 m0, s66
	v_lshl_add_u64 v[64:65], s[42:43], 0, v[200:201]
	global_load_lds_dwordx4 v[64:65], off
	v_lshl_add_u64 v[64:65], s[42:43], 0, v[144:145]
	s_mov_b32 m0, s67
	s_nop 0
	global_load_lds_dwordx4 v[64:65], off
	s_waitcnt vmcnt(6)
	s_barrier
	v_mfma_f32_16x16x32_bf16 v[52:55], v[218:221], v[174:177], v[52:55]
	v_mfma_f32_16x16x32_bf16 v[48:51], v[230:233], v[174:177], v[48:51]
	v_mfma_f32_16x16x32_bf16 v[36:39], v[218:221], v[182:185], v[36:39]
	v_mfma_f32_16x16x32_bf16 v[32:35], v[230:233], v[182:185], v[32:35]
	v_mfma_f32_16x16x32_bf16 v[20:23], v[218:221], v[190:193], v[20:23]
	v_mfma_f32_16x16x32_bf16 v[16:19], v[230:233], v[190:193], v[16:19]
	v_mfma_f32_16x16x32_bf16 v[4:7], v[218:221], v[210:213], v[4:7]
	v_mfma_f32_16x16x32_bf16 v[0:3], v[230:233], v[210:213], v[0:3]
	v_mfma_f32_16x16x32_bf16 v[52:55], v[222:225], v[178:181], v[52:55]
	v_mfma_f32_16x16x32_bf16 v[48:51], v[248:251], v[178:181], v[48:51]
	v_mfma_f32_16x16x32_bf16 v[36:39], v[222:225], v[186:189], v[36:39]
	v_mfma_f32_16x16x32_bf16 v[32:35], v[248:251], v[186:189], v[32:35]
	v_mfma_f32_16x16x32_bf16 v[20:23], v[222:225], v[194:197], v[20:23]
	v_mfma_f32_16x16x32_bf16 v[16:19], v[248:251], v[194:197], v[16:19]
	v_mfma_f32_16x16x32_bf16 v[4:7], v[222:225], v[214:217], v[4:7]
	v_mfma_f32_16x16x32_bf16 v[0:3], v[248:251], v[214:217], v[0:3]
	s_add_i32 vcc_hi, vcc_hi, 2
	s_add_u32 s46, s46, 0x100
	s_addc_u32 s47, s47, 0
	s_add_u32 s97, s97, 0x100
	s_addc_u32 vcc_lo, vcc_lo, 0
	s_cmp_gt_u32 vcc_hi, 13
	s_barrier
	s_cbranch_scc0 .LBB0_158
	s_min_i32 s1, s29, 6
	s_lshl_b32 s1, s1, 8
	v_or_b32_e32 v65, 0x700, v172
	v_add_u32_e32 v64, s1, v155
	v_add_u32_e32 v65, s1, v65
	v_lshl_add_u32 v64, v64, 2, v246
	v_lshl_add_u32 v65, v65, 2, v246
	ds_read_b32 v174, v64 offset:0
	ds_read_b32 v166, v64 offset:64
	ds_read_b32 v164, v64 offset:128
	ds_read_b32 v162, v64 offset:192
	ds_read_b32 v160, v64 offset:512
	ds_read_b32 v158, v64 offset:576
	ds_read_b32 v156, v64 offset:640
	ds_read_b32 v154, v64 offset:704
	ds_read_b128 v[76:79], v65 offset:0
	ds_read_b128 v[72:75], v65 offset:16
	ds_read_b128 v[68:71], v65 offset:512
	ds_read_b128 v[64:67], v65 offset:528
	v_lshl_or_b32 v168, s28, 7, v172
	s_waitcnt lgkmcnt(0)
	v_lshl_add_u32 v173, s44, 8, v155
	v_pk_fma_f32 v[140:141], v[140:141], v[174:175], v[76:77] op_sel_hi:[1,0,1]
	v_pk_fma_f32 v[142:143], v[142:143], v[174:175], v[78:79] op_sel_hi:[1,0,1]
	v_pk_fma_f32 v[138:139], v[138:139], v[174:175], v[74:75] op_sel_hi:[1,0,1]
	v_pk_fma_f32 v[136:137], v[136:137], v[174:175], v[72:73] op_sel_hi:[1,0,1]
	v_pk_fma_f32 v[134:135], v[134:135], v[174:175], v[70:71] op_sel_hi:[1,0,1]
	v_pk_fma_f32 v[132:133], v[132:133], v[174:175], v[68:69] op_sel_hi:[1,0,1]
	v_pk_fma_f32 v[130:131], v[130:131], v[174:175], v[66:67] op_sel_hi:[1,0,1]
	v_pk_fma_f32 v[128:129], v[128:129], v[174:175], v[64:65] op_sel_hi:[1,0,1]
	v_mul_f32_e32 v174, 0xbfb8aa3b, v140
	v_mul_f32_e32 v175, 0xbfb8aa3b, v141
	v_exp_f32_e32 v174, v174
	v_exp_f32_e32 v175, v175
	v_ashrrev_i32_e32 v169, 31, v168
	v_pk_fma_f32 v[124:125], v[124:125], v[166:167], v[76:77] op_sel_hi:[1,0,1]
	v_add_f32_e32 v174, 1.0, v174
	v_add_f32_e32 v175, 1.0, v175
	v_rcp_f32_e32 v174, v174
	v_rcp_f32_e32 v175, v175
	v_pk_fma_f32 v[116:117], v[116:117], v[166:167], v[68:69] op_sel_hi:[1,0,1]
	v_pk_fma_f32 v[126:127], v[126:127], v[166:167], v[78:79] op_sel_hi:[1,0,1]
	v_pk_fma_f32 v[118:119], v[118:119], v[166:167], v[70:71] op_sel_hi:[1,0,1]
	v_pk_mul_f32 v[140:141], v[140:141], v[174:175]
	v_pk_fma_f32 v[120:121], v[120:121], v[166:167], v[72:73] op_sel_hi:[1,0,1]
	v_pk_mul_f32 v[132:133], v[132:133], v[140:141]
	v_pk_fma_f32 v[122:123], v[122:123], v[166:167], v[74:75] op_sel_hi:[1,0,1]
	v_cvt_pk_bf16_f32 v132, v132, v133
	v_mul_f32_e32 v133, 0xbfb8aa3b, v142
	v_exp_f32_e32 v133, v133
	v_pk_fma_f32 v[108:109], v[108:109], v[164:165], v[76:77] op_sel_hi:[1,0,1]
	v_pk_fma_f32 v[100:101], v[100:101], v[164:165], v[68:69] op_sel_hi:[1,0,1]
	v_pk_fma_f32 v[110:111], v[110:111], v[164:165], v[78:79] op_sel_hi:[1,0,1]
	v_add_f32_e32 v133, 1.0, v133
	v_rcp_f32_e32 v140, v133
	v_mul_f32_e32 v133, 0xbfb8aa3b, v143
	v_exp_f32_e32 v133, v133
	v_pk_fma_f32 v[102:103], v[102:103], v[164:165], v[70:71] op_sel_hi:[1,0,1]
	v_pk_fma_f32 v[104:105], v[104:105], v[164:165], v[72:73] op_sel_hi:[1,0,1]
	v_pk_fma_f32 v[106:107], v[106:107], v[164:165], v[74:75] op_sel_hi:[1,0,1]
	v_add_f32_e32 v133, 1.0, v133
	v_rcp_f32_e32 v141, v133
	v_pk_fma_f32 v[92:93], v[92:93], v[162:163], v[76:77] op_sel_hi:[1,0,1]
	v_pk_fma_f32 v[84:85], v[84:85], v[162:163], v[68:69] op_sel_hi:[1,0,1]
	v_pk_fma_f32 v[94:95], v[94:95], v[162:163], v[78:79] op_sel_hi:[1,0,1]
	v_pk_mul_f32 v[140:141], v[142:143], v[140:141]
	v_pk_fma_f32 v[86:87], v[86:87], v[162:163], v[70:71] op_sel_hi:[1,0,1]
	v_pk_mul_f32 v[134:135], v[134:135], v[140:141]
	v_pk_fma_f32 v[88:89], v[88:89], v[162:163], v[72:73] op_sel_hi:[1,0,1]
	v_cvt_pk_bf16_f32 v133, v134, v135
	v_mul_f32_e32 v134, 0xbfb8aa3b, v136
	v_mul_f32_e32 v135, 0xbfb8aa3b, v137
	v_exp_f32_e32 v134, v134
	v_exp_f32_e32 v135, v135
	v_pk_fma_f32 v[90:91], v[90:91], v[162:163], v[74:75] op_sel_hi:[1,0,1]
	v_pk_fma_f32 v[60:61], v[60:61], v[160:161], v[76:77] op_sel_hi:[1,0,1]
	v_add_f32_e32 v134, 1.0, v134
	v_add_f32_e32 v135, 1.0, v135
	v_rcp_f32_e32 v134, v134
	v_rcp_f32_e32 v135, v135
	v_pk_fma_f32 v[52:53], v[52:53], v[160:161], v[68:69] op_sel_hi:[1,0,1]
	v_pk_fma_f32 v[62:63], v[62:63], v[160:161], v[78:79] op_sel_hi:[1,0,1]
	v_pk_fma_f32 v[54:55], v[54:55], v[160:161], v[70:71] op_sel_hi:[1,0,1]
	v_pk_mul_f32 v[134:135], v[136:137], v[134:135]
	v_pk_fma_f32 v[56:57], v[56:57], v[160:161], v[72:73] op_sel_hi:[1,0,1]
	v_pk_mul_f32 v[128:129], v[128:129], v[134:135]
	v_pk_fma_f32 v[58:59], v[58:59], v[160:161], v[74:75] op_sel_hi:[1,0,1]
	v_cvt_pk_bf16_f32 v134, v128, v129
	v_mul_f32_e32 v128, 0xbfb8aa3b, v138
	v_mul_f32_e32 v129, 0xbfb8aa3b, v139
	v_exp_f32_e32 v128, v128
	v_exp_f32_e32 v129, v129
	v_pk_fma_f32 v[44:45], v[44:45], v[158:159], v[76:77] op_sel_hi:[1,0,1]
	v_pk_fma_f32 v[36:37], v[36:37], v[158:159], v[68:69] op_sel_hi:[1,0,1]
	v_add_f32_e32 v128, 1.0, v128
	v_add_f32_e32 v129, 1.0, v129
	v_rcp_f32_e32 v128, v128
	v_rcp_f32_e32 v129, v129
	v_pk_fma_f32 v[46:47], v[46:47], v[158:159], v[78:79] op_sel_hi:[1,0,1]
	v_pk_fma_f32 v[38:39], v[38:39], v[158:159], v[70:71] op_sel_hi:[1,0,1]
	v_pk_fma_f32 v[40:41], v[40:41], v[158:159], v[72:73] op_sel_hi:[1,0,1]
	v_pk_mul_f32 v[128:129], v[138:139], v[128:129]
	v_pk_fma_f32 v[42:43], v[42:43], v[158:159], v[74:75] op_sel_hi:[1,0,1]
	v_pk_mul_f32 v[128:129], v[130:131], v[128:129]
	v_lshlrev_b64 v[130:131], 1, v[168:169]
	v_cvt_pk_bf16_f32 v135, v128, v129
	v_mov_b64_e32 v[128:129], s[24:25]
	v_mad_i64_i32 v[136:137], s[28:29], v173, s92, v[128:129]
	v_lshl_add_u64 v[136:137], v[136:137], 0, v[130:131]
	global_store_dwordx4 v[136:137], v[132:135], off
	v_pk_fma_f32 v[28:29], v[28:29], v[156:157], v[76:77] op_sel_hi:[1,0,1]
	v_pk_fma_f32 v[20:21], v[20:21], v[156:157], v[68:69] op_sel_hi:[1,0,1]
	v_pk_fma_f32 v[132:133], v[114:115], v[166:167], v[66:67] op_sel_hi:[1,0,1]
	v_pk_fma_f32 v[114:115], v[112:113], v[166:167], v[64:65] op_sel_hi:[1,0,1]
	v_mul_f32_e32 v112, 0xbfb8aa3b, v124
	v_mul_f32_e32 v113, 0xbfb8aa3b, v125
	v_exp_f32_e32 v112, v112
	v_exp_f32_e32 v113, v113
	v_or_b32_e32 v134, 16, v173
	v_pk_fma_f32 v[30:31], v[30:31], v[156:157], v[78:79] op_sel_hi:[1,0,1]
	v_add_f32_e32 v112, 1.0, v112
	v_add_f32_e32 v113, 1.0, v113
	v_rcp_f32_e32 v112, v112
	v_rcp_f32_e32 v113, v113
	v_pk_fma_f32 v[22:23], v[22:23], v[156:157], v[70:71] op_sel_hi:[1,0,1]
	v_pk_fma_f32 v[24:25], v[24:25], v[156:157], v[72:73] op_sel_hi:[1,0,1]
	v_pk_fma_f32 v[26:27], v[26:27], v[156:157], v[74:75] op_sel_hi:[1,0,1]
	v_pk_mul_f32 v[112:113], v[124:125], v[112:113]
	v_pk_fma_f32 v[12:13], v[12:13], v[154:155], v[76:77] op_sel_hi:[1,0,1]
	v_pk_mul_f32 v[112:113], v[116:117], v[112:113]
	v_pk_fma_f32 v[4:5], v[4:5], v[154:155], v[68:69] op_sel_hi:[1,0,1]
	v_cvt_pk_bf16_f32 v112, v112, v113
	v_mul_f32_e32 v113, 0xbfb8aa3b, v126
	v_exp_f32_e32 v113, v113
	v_pk_fma_f32 v[14:15], v[14:15], v[154:155], v[78:79] op_sel_hi:[1,0,1]
	v_pk_fma_f32 v[6:7], v[6:7], v[154:155], v[70:71] op_sel_hi:[1,0,1]
	v_pk_fma_f32 v[8:9], v[8:9], v[154:155], v[72:73] op_sel_hi:[1,0,1]
	v_add_f32_e32 v113, 1.0, v113
	v_rcp_f32_e32 v116, v113
	v_mul_f32_e32 v113, 0xbfb8aa3b, v127
	v_exp_f32_e32 v113, v113
	v_pk_fma_f32 v[10:11], v[10:11], v[154:155], v[74:75] op_sel_hi:[1,0,1]
	s_and_b64 vcc, exec, s[36:37]
	s_mov_b32 s44, s2
	v_add_f32_e32 v113, 1.0, v113
	v_rcp_f32_e32 v117, v113
	s_mov_b64 s[48:49], s[40:41]
	s_mov_b64 s[46:47], s[38:39]
	v_pk_mul_f32 v[116:117], v[126:127], v[116:117]
	s_nop 0
	v_pk_mul_f32 v[116:117], v[118:119], v[116:117]
	s_nop 0
	v_cvt_pk_bf16_f32 v113, v116, v117
	v_mul_f32_e32 v116, 0xbfb8aa3b, v120
	v_mul_f32_e32 v117, 0xbfb8aa3b, v121
	v_exp_f32_e32 v116, v116
	v_exp_f32_e32 v117, v117
	v_add_f32_e32 v116, 1.0, v116
	v_add_f32_e32 v117, 1.0, v117
	v_rcp_f32_e32 v116, v116
	v_rcp_f32_e32 v117, v117
	s_nop 0
	v_pk_mul_f32 v[116:117], v[120:121], v[116:117]
	s_nop 0
	v_pk_mul_f32 v[114:115], v[114:115], v[116:117]
	s_nop 0
	v_cvt_pk_bf16_f32 v114, v114, v115
	v_mul_f32_e32 v115, 0xbfb8aa3b, v122
	v_exp_f32_e32 v115, v115
	s_nop 0
	v_add_f32_e32 v115, 1.0, v115
	v_rcp_f32_e32 v116, v115
	v_mul_f32_e32 v115, 0xbfb8aa3b, v123
	v_exp_f32_e32 v115, v115
	s_nop 0
	v_add_f32_e32 v115, 1.0, v115
	v_rcp_f32_e32 v117, v115
	s_nop 0
	v_pk_mul_f32 v[116:117], v[122:123], v[116:117]
	s_nop 0
	v_pk_mul_f32 v[116:117], v[132:133], v[116:117]
	s_nop 0
	v_cvt_pk_bf16_f32 v115, v116, v117
	v_mad_i64_i32 v[116:117], s[28:29], v134, s92, v[128:129]
	v_lshl_add_u64 v[116:117], v[116:117], 0, v[130:131]
	global_store_dwordx4 v[116:117], v[112:115], off
	s_nop 1
	v_pk_fma_f32 v[112:113], v[98:99], v[164:165], v[66:67] op_sel_hi:[1,0,1]
	v_pk_fma_f32 v[98:99], v[96:97], v[164:165], v[64:65] op_sel_hi:[1,0,1]
	v_mul_f32_e32 v96, 0xbfb8aa3b, v108
	v_mul_f32_e32 v97, 0xbfb8aa3b, v109
	v_exp_f32_e32 v96, v96
	v_exp_f32_e32 v97, v97
	v_or_b32_e32 v114, 32, v173
	v_add_f32_e32 v96, 1.0, v96
	v_add_f32_e32 v97, 1.0, v97
	v_rcp_f32_e32 v96, v96
	v_rcp_f32_e32 v97, v97
	s_nop 0
	v_pk_mul_f32 v[96:97], v[108:109], v[96:97]
	s_nop 0
	v_pk_mul_f32 v[96:97], v[100:101], v[96:97]
	s_nop 0
	v_cvt_pk_bf16_f32 v96, v96, v97
	v_mul_f32_e32 v97, 0xbfb8aa3b, v110
	v_exp_f32_e32 v97, v97
	s_nop 0
	v_add_f32_e32 v97, 1.0, v97
	v_rcp_f32_e32 v100, v97
	v_mul_f32_e32 v97, 0xbfb8aa3b, v111
	v_exp_f32_e32 v97, v97
	s_nop 0
	v_add_f32_e32 v97, 1.0, v97
	v_rcp_f32_e32 v101, v97
	s_nop 0
	v_pk_mul_f32 v[100:101], v[110:111], v[100:101]
	s_nop 0
	v_pk_mul_f32 v[100:101], v[102:103], v[100:101]
	s_nop 0
	v_cvt_pk_bf16_f32 v97, v100, v101
	v_mul_f32_e32 v100, 0xbfb8aa3b, v104
	v_mul_f32_e32 v101, 0xbfb8aa3b, v105
	v_exp_f32_e32 v100, v100
	v_exp_f32_e32 v101, v101
	v_add_f32_e32 v100, 1.0, v100
	v_add_f32_e32 v101, 1.0, v101
	v_rcp_f32_e32 v100, v100
	v_rcp_f32_e32 v101, v101
	s_nop 0
	v_pk_mul_f32 v[100:101], v[104:105], v[100:101]
	s_nop 0
	v_pk_mul_f32 v[98:99], v[98:99], v[100:101]
	s_nop 0
	v_cvt_pk_bf16_f32 v98, v98, v99
	v_mul_f32_e32 v99, 0xbfb8aa3b, v106
	v_exp_f32_e32 v99, v99
	s_nop 0
	v_add_f32_e32 v99, 1.0, v99
	v_rcp_f32_e32 v100, v99
	v_mul_f32_e32 v99, 0xbfb8aa3b, v107
	v_exp_f32_e32 v99, v99
	s_nop 0
	v_add_f32_e32 v99, 1.0, v99
	v_rcp_f32_e32 v101, v99
	s_nop 0
	v_pk_mul_f32 v[100:101], v[106:107], v[100:101]
	s_nop 0
	v_pk_mul_f32 v[100:101], v[112:113], v[100:101]
	s_nop 0
	v_cvt_pk_bf16_f32 v99, v100, v101
	v_mad_i64_i32 v[100:101], s[28:29], v114, s92, v[128:129]
	v_lshl_add_u64 v[100:101], v[100:101], 0, v[130:131]
	global_store_dwordx4 v[100:101], v[96:99], off
	s_nop 1
	v_pk_fma_f32 v[96:97], v[82:83], v[162:163], v[66:67] op_sel_hi:[1,0,1]
	v_pk_fma_f32 v[82:83], v[80:81], v[162:163], v[64:65] op_sel_hi:[1,0,1]
	v_mul_f32_e32 v80, 0xbfb8aa3b, v92
	v_mul_f32_e32 v81, 0xbfb8aa3b, v93
	v_exp_f32_e32 v80, v80
	v_exp_f32_e32 v81, v81
	v_or_b32_e32 v98, 48, v173
	v_add_f32_e32 v80, 1.0, v80
	v_add_f32_e32 v81, 1.0, v81
	v_rcp_f32_e32 v80, v80
	v_rcp_f32_e32 v81, v81
	s_nop 0
	v_pk_mul_f32 v[80:81], v[92:93], v[80:81]
	s_nop 0
	v_pk_mul_f32 v[80:81], v[84:85], v[80:81]
	s_nop 0
	v_cvt_pk_bf16_f32 v80, v80, v81
	v_mul_f32_e32 v81, 0xbfb8aa3b, v94
	v_exp_f32_e32 v81, v81
	s_nop 0
	v_add_f32_e32 v81, 1.0, v81
	v_rcp_f32_e32 v84, v81
	v_mul_f32_e32 v81, 0xbfb8aa3b, v95
	v_exp_f32_e32 v81, v81
	s_nop 0
	v_add_f32_e32 v81, 1.0, v81
	v_rcp_f32_e32 v85, v81
	s_nop 0
	v_pk_mul_f32 v[84:85], v[94:95], v[84:85]
	s_nop 0
	v_pk_mul_f32 v[84:85], v[86:87], v[84:85]
	s_nop 0
	v_cvt_pk_bf16_f32 v81, v84, v85
	v_mul_f32_e32 v84, 0xbfb8aa3b, v88
	v_mul_f32_e32 v85, 0xbfb8aa3b, v89
	v_exp_f32_e32 v84, v84
	v_exp_f32_e32 v85, v85
	v_add_f32_e32 v84, 1.0, v84
	v_add_f32_e32 v85, 1.0, v85
	v_rcp_f32_e32 v84, v84
	v_rcp_f32_e32 v85, v85
	s_nop 0
	v_pk_mul_f32 v[84:85], v[88:89], v[84:85]
	s_nop 0
	v_pk_mul_f32 v[82:83], v[82:83], v[84:85]
	s_nop 0
	v_cvt_pk_bf16_f32 v82, v82, v83
	v_mul_f32_e32 v83, 0xbfb8aa3b, v90
	v_exp_f32_e32 v83, v83
	s_nop 0
	v_add_f32_e32 v83, 1.0, v83
	v_rcp_f32_e32 v84, v83
	v_mul_f32_e32 v83, 0xbfb8aa3b, v91
	v_exp_f32_e32 v83, v83
	s_nop 0
	v_add_f32_e32 v83, 1.0, v83
	v_rcp_f32_e32 v85, v83
	s_nop 0
	v_pk_mul_f32 v[84:85], v[90:91], v[84:85]
	s_nop 0
	v_pk_mul_f32 v[84:85], v[96:97], v[84:85]
	s_nop 0
	v_cvt_pk_bf16_f32 v83, v84, v85
	v_mad_i64_i32 v[84:85], s[28:29], v98, s92, v[128:129]
	v_lshl_add_u64 v[84:85], v[84:85], 0, v[130:131]
	global_store_dwordx4 v[84:85], v[80:83], off
	s_nop 1
	v_pk_fma_f32 v[80:81], v[50:51], v[160:161], v[66:67] op_sel_hi:[1,0,1]
	v_pk_fma_f32 v[50:51], v[48:49], v[160:161], v[64:65] op_sel_hi:[1,0,1]
	v_mul_f32_e32 v48, 0xbfb8aa3b, v60
	v_mul_f32_e32 v49, 0xbfb8aa3b, v61
	v_exp_f32_e32 v48, v48
	v_exp_f32_e32 v49, v49
	v_add_u32_e32 v82, 0x80, v173
	v_add_f32_e32 v48, 1.0, v48
	v_add_f32_e32 v49, 1.0, v49
	v_rcp_f32_e32 v48, v48
	v_rcp_f32_e32 v49, v49
	s_nop 0
	v_pk_mul_f32 v[48:49], v[60:61], v[48:49]
	s_nop 0
	v_pk_mul_f32 v[48:49], v[52:53], v[48:49]
	s_nop 0
	v_cvt_pk_bf16_f32 v48, v48, v49
	v_mul_f32_e32 v49, 0xbfb8aa3b, v62
	v_exp_f32_e32 v49, v49
	s_nop 0
	v_add_f32_e32 v49, 1.0, v49
	v_rcp_f32_e32 v52, v49
	v_mul_f32_e32 v49, 0xbfb8aa3b, v63
	v_exp_f32_e32 v49, v49
	s_nop 0
	v_add_f32_e32 v49, 1.0, v49
	v_rcp_f32_e32 v53, v49
	s_nop 0
	v_pk_mul_f32 v[52:53], v[62:63], v[52:53]
	s_nop 0
	v_pk_mul_f32 v[52:53], v[54:55], v[52:53]
	s_nop 0
	v_cvt_pk_bf16_f32 v49, v52, v53
	v_mul_f32_e32 v52, 0xbfb8aa3b, v56
	v_mul_f32_e32 v53, 0xbfb8aa3b, v57
	v_exp_f32_e32 v52, v52
	v_exp_f32_e32 v53, v53
	v_add_f32_e32 v52, 1.0, v52
	v_add_f32_e32 v53, 1.0, v53
	v_rcp_f32_e32 v52, v52
	v_rcp_f32_e32 v53, v53
	s_nop 0
	v_pk_mul_f32 v[52:53], v[56:57], v[52:53]
	s_nop 0
	v_pk_mul_f32 v[50:51], v[50:51], v[52:53]
	s_nop 0
	v_cvt_pk_bf16_f32 v50, v50, v51
	v_mul_f32_e32 v51, 0xbfb8aa3b, v58
	v_exp_f32_e32 v51, v51
	s_nop 0
	v_add_f32_e32 v51, 1.0, v51
	v_rcp_f32_e32 v52, v51
	v_mul_f32_e32 v51, 0xbfb8aa3b, v59
	v_exp_f32_e32 v51, v51
	s_nop 0
	v_add_f32_e32 v51, 1.0, v51
	v_rcp_f32_e32 v53, v51
	s_nop 0
	v_pk_mul_f32 v[52:53], v[58:59], v[52:53]
	s_nop 0
	v_pk_mul_f32 v[52:53], v[80:81], v[52:53]
	s_nop 0
	v_cvt_pk_bf16_f32 v51, v52, v53
	v_mad_i64_i32 v[52:53], s[28:29], v82, s92, v[128:129]
	v_lshl_add_u64 v[52:53], v[52:53], 0, v[130:131]
	global_store_dwordx4 v[52:53], v[48:51], off
	s_nop 1
	v_pk_fma_f32 v[48:49], v[34:35], v[158:159], v[66:67] op_sel_hi:[1,0,1]
	v_pk_fma_f32 v[34:35], v[32:33], v[158:159], v[64:65] op_sel_hi:[1,0,1]
	v_mul_f32_e32 v32, 0xbfb8aa3b, v44
	v_mul_f32_e32 v33, 0xbfb8aa3b, v45
	v_exp_f32_e32 v32, v32
	v_exp_f32_e32 v33, v33
	v_add_u32_e32 v50, 0x90, v173
	v_add_f32_e32 v32, 1.0, v32
	v_add_f32_e32 v33, 1.0, v33
	v_rcp_f32_e32 v32, v32
	v_rcp_f32_e32 v33, v33
	s_nop 0
	v_pk_mul_f32 v[32:33], v[44:45], v[32:33]
	s_nop 0
	v_pk_mul_f32 v[32:33], v[36:37], v[32:33]
	s_nop 0
	v_cvt_pk_bf16_f32 v32, v32, v33
	v_mul_f32_e32 v33, 0xbfb8aa3b, v46
	v_exp_f32_e32 v33, v33
	s_nop 0
	v_add_f32_e32 v33, 1.0, v33
	v_rcp_f32_e32 v36, v33
	v_mul_f32_e32 v33, 0xbfb8aa3b, v47
	v_exp_f32_e32 v33, v33
	s_nop 0
	v_add_f32_e32 v33, 1.0, v33
	v_rcp_f32_e32 v37, v33
	s_nop 0
	v_pk_mul_f32 v[36:37], v[46:47], v[36:37]
	s_nop 0
	v_pk_mul_f32 v[36:37], v[38:39], v[36:37]
	s_nop 0
	v_cvt_pk_bf16_f32 v33, v36, v37
	v_mul_f32_e32 v36, 0xbfb8aa3b, v40
	v_mul_f32_e32 v37, 0xbfb8aa3b, v41
	v_exp_f32_e32 v36, v36
	v_exp_f32_e32 v37, v37
	v_add_f32_e32 v36, 1.0, v36
	v_add_f32_e32 v37, 1.0, v37
	v_rcp_f32_e32 v36, v36
	v_rcp_f32_e32 v37, v37
	s_nop 0
	v_pk_mul_f32 v[36:37], v[40:41], v[36:37]
	s_nop 0
	v_pk_mul_f32 v[34:35], v[34:35], v[36:37]
	s_nop 0
	v_cvt_pk_bf16_f32 v34, v34, v35
	v_mul_f32_e32 v35, 0xbfb8aa3b, v42
	v_exp_f32_e32 v35, v35
	s_nop 0
	v_add_f32_e32 v35, 1.0, v35
	v_rcp_f32_e32 v36, v35
	v_mul_f32_e32 v35, 0xbfb8aa3b, v43
	v_exp_f32_e32 v35, v35
	s_nop 0
	v_add_f32_e32 v35, 1.0, v35
	v_rcp_f32_e32 v37, v35
	s_nop 0
	v_pk_mul_f32 v[36:37], v[42:43], v[36:37]
	s_nop 0
	v_pk_mul_f32 v[36:37], v[48:49], v[36:37]
	s_nop 0
	v_cvt_pk_bf16_f32 v35, v36, v37
	v_mad_i64_i32 v[36:37], s[28:29], v50, s92, v[128:129]
	v_lshl_add_u64 v[36:37], v[36:37], 0, v[130:131]
	global_store_dwordx4 v[36:37], v[32:35], off
	s_nop 1
	v_pk_fma_f32 v[32:33], v[18:19], v[156:157], v[66:67] op_sel_hi:[1,0,1]
	v_pk_fma_f32 v[18:19], v[16:17], v[156:157], v[64:65] op_sel_hi:[1,0,1]
	v_mul_f32_e32 v16, 0xbfb8aa3b, v28
	v_mul_f32_e32 v17, 0xbfb8aa3b, v29
	v_exp_f32_e32 v16, v16
	v_exp_f32_e32 v17, v17
	v_add_u32_e32 v34, 0xa0, v173
	v_add_f32_e32 v16, 1.0, v16
	v_add_f32_e32 v17, 1.0, v17
	v_rcp_f32_e32 v16, v16
	v_rcp_f32_e32 v17, v17
	s_nop 0
	v_pk_mul_f32 v[16:17], v[28:29], v[16:17]
	s_nop 0
	v_pk_mul_f32 v[16:17], v[20:21], v[16:17]
	s_nop 0
	v_cvt_pk_bf16_f32 v16, v16, v17
	v_mul_f32_e32 v17, 0xbfb8aa3b, v30
	v_exp_f32_e32 v17, v17
	s_nop 0
	v_add_f32_e32 v17, 1.0, v17
	v_rcp_f32_e32 v20, v17
	v_mul_f32_e32 v17, 0xbfb8aa3b, v31
	v_exp_f32_e32 v17, v17
	s_nop 0
	v_add_f32_e32 v17, 1.0, v17
	v_rcp_f32_e32 v21, v17
	s_nop 0
	v_pk_mul_f32 v[20:21], v[30:31], v[20:21]
	s_nop 0
	v_pk_mul_f32 v[20:21], v[22:23], v[20:21]
	s_nop 0
	v_cvt_pk_bf16_f32 v17, v20, v21
	v_mul_f32_e32 v20, 0xbfb8aa3b, v24
	v_mul_f32_e32 v21, 0xbfb8aa3b, v25
	v_exp_f32_e32 v20, v20
	v_exp_f32_e32 v21, v21
	v_add_f32_e32 v20, 1.0, v20
	v_add_f32_e32 v21, 1.0, v21
	v_rcp_f32_e32 v20, v20
	v_rcp_f32_e32 v21, v21
	s_nop 0
	v_pk_mul_f32 v[20:21], v[24:25], v[20:21]
	s_nop 0
	v_pk_mul_f32 v[18:19], v[18:19], v[20:21]
	s_nop 0
	v_cvt_pk_bf16_f32 v18, v18, v19
	v_mul_f32_e32 v19, 0xbfb8aa3b, v26
	v_exp_f32_e32 v19, v19
	s_nop 0
	v_add_f32_e32 v19, 1.0, v19
	v_rcp_f32_e32 v20, v19
	v_mul_f32_e32 v19, 0xbfb8aa3b, v27
	v_exp_f32_e32 v19, v19
	s_nop 0
	v_add_f32_e32 v19, 1.0, v19
	v_rcp_f32_e32 v21, v19
	s_nop 0
	v_pk_mul_f32 v[20:21], v[26:27], v[20:21]
	s_nop 0
	v_pk_mul_f32 v[20:21], v[32:33], v[20:21]
	s_nop 0
	v_cvt_pk_bf16_f32 v19, v20, v21
	v_mad_i64_i32 v[20:21], s[28:29], v34, s92, v[128:129]
	v_lshl_add_u64 v[20:21], v[20:21], 0, v[130:131]
	global_store_dwordx4 v[20:21], v[16:19], off
	s_nop 1
	v_pk_fma_f32 v[16:17], v[2:3], v[154:155], v[66:67] op_sel_hi:[1,0,1]
	v_pk_fma_f32 v[2:3], v[0:1], v[154:155], v[64:65] op_sel_hi:[1,0,1]
	v_mul_f32_e32 v0, 0xbfb8aa3b, v12
	v_mul_f32_e32 v1, 0xbfb8aa3b, v13
	v_exp_f32_e32 v0, v0
	v_exp_f32_e32 v1, v1
	v_add_u32_e32 v18, 0xb0, v173
	v_add_f32_e32 v0, 1.0, v0
	v_add_f32_e32 v1, 1.0, v1
	v_rcp_f32_e32 v0, v0
	v_rcp_f32_e32 v1, v1
	s_nop 0
	v_pk_mul_f32 v[0:1], v[12:13], v[0:1]
	s_nop 0
	v_pk_mul_f32 v[0:1], v[4:5], v[0:1]
	s_nop 0
	v_cvt_pk_bf16_f32 v0, v0, v1
	v_mul_f32_e32 v1, 0xbfb8aa3b, v14
	v_exp_f32_e32 v1, v1
	s_nop 0
	v_add_f32_e32 v1, 1.0, v1
	v_rcp_f32_e32 v4, v1
	v_mul_f32_e32 v1, 0xbfb8aa3b, v15
	v_exp_f32_e32 v1, v1
	s_nop 0
	v_add_f32_e32 v1, 1.0, v1
	v_rcp_f32_e32 v5, v1
	s_nop 0
	v_pk_mul_f32 v[4:5], v[14:15], v[4:5]
	s_nop 0
	v_pk_mul_f32 v[4:5], v[6:7], v[4:5]
	s_nop 0
	v_cvt_pk_bf16_f32 v1, v4, v5
	v_mul_f32_e32 v4, 0xbfb8aa3b, v8
	v_mul_f32_e32 v5, 0xbfb8aa3b, v9
	v_exp_f32_e32 v4, v4
	v_exp_f32_e32 v5, v5
	v_add_f32_e32 v4, 1.0, v4
	v_add_f32_e32 v5, 1.0, v5
	v_rcp_f32_e32 v4, v4
	v_rcp_f32_e32 v5, v5
	s_nop 0
	v_pk_mul_f32 v[4:5], v[8:9], v[4:5]
	s_nop 0
	v_pk_mul_f32 v[2:3], v[2:3], v[4:5]
	s_nop 0
	v_cvt_pk_bf16_f32 v2, v2, v3
	v_mul_f32_e32 v3, 0xbfb8aa3b, v10
	v_exp_f32_e32 v3, v3
	s_nop 0
	v_add_f32_e32 v3, 1.0, v3
	v_rcp_f32_e32 v4, v3
	v_mul_f32_e32 v3, 0xbfb8aa3b, v11
	v_exp_f32_e32 v3, v3
	s_nop 0
	v_add_f32_e32 v3, 1.0, v3
	v_rcp_f32_e32 v5, v3
	s_nop 0
	v_pk_mul_f32 v[4:5], v[10:11], v[4:5]
	s_nop 0
	v_pk_mul_f32 v[4:5], v[16:17], v[4:5]
	s_nop 0
	v_cvt_pk_bf16_f32 v3, v4, v5
	v_mad_i64_i32 v[4:5], s[28:29], v18, s92, v[128:129]
	v_lshl_add_u64 v[4:5], v[4:5], 0, v[130:131]
	s_mov_b32 s28, s0
	s_mov_b32 s29, s73
	global_store_dwordx4 v[4:5], v[0:3], off
	s_cbranch_vccz .LBB0_155
	s_waitcnt vmcnt(0)
	s_cmpk_gt_u32 s52, 0xff
	s_mov_b64 s[66:67], 0
	s_cbranch_scc1 .LBB0_162
	s_barrier

.LBB0_721:
	s_add_u32 s48, s46, 0xfffc0080
	s_addc_u32 s49, s47, -1
	s_add_i32 m0, s53, 0xc000
	s_add_i32 s54, s53, 0xe000
	s_cmp_eq_u32 vcc_lo, 12
	s_cselect_b32 s51, s39, s49
	s_cselect_b32 s50, s73, s48
	ds_read_b128 v[128:131], v162 offset:0
	ds_read_b128 v[132:135], v162 offset:1024
	ds_read_b128 v[136:139], v162 offset:2048
	ds_read_b128 v[140:143], v162 offset:3072
	v_lshl_add_u64 v[198:199], s[46:47], 0, v[150:151]
	ds_read_b128 v[158:161], v157 offset:0
	ds_read_b128 v[170:173], v157 offset:1024
	ds_read_b128 v[174:177], v157 offset:2048
	ds_read_b128 v[178:181], v157 offset:3072
	ds_read_b128 v[182:185], v157 offset:4096
	ds_read_b128 v[186:189], v157 offset:5120
	ds_read_b128 v[190:193], v157 offset:6144
	ds_read_b128 v[194:197], v157 offset:7168
	global_load_lds_dwordx4 v[198:199], off
	v_lshl_add_u64 v[198:199], s[46:47], 0, v[152:153]
	s_mov_b32 m0, s54
	s_cselect_b32 s49, s3, s97
	global_load_lds_dwordx4 v[198:199], off
	s_waitcnt lgkmcnt(8)
	s_barrier
	s_waitcnt lgkmcnt(0)
	s_waitcnt lgkmcnt(0)
	s_cselect_b32 s48, s94, s96
	v_mfma_f32_16x16x32_bf16 v[124:127], v[128:131], v[158:161], v[124:127]
	v_mfma_f32_16x16x32_bf16 v[120:123], v[136:139], v[158:161], v[120:123]
	v_mfma_f32_16x16x32_bf16 v[116:119], v[128:131], v[174:177], v[116:119]
	v_mfma_f32_16x16x32_bf16 v[108:111], v[136:139], v[174:177], v[108:111]
	v_mfma_f32_16x16x32_bf16 v[100:103], v[128:131], v[182:185], v[100:103]
	v_mfma_f32_16x16x32_bf16 v[92:95], v[136:139], v[182:185], v[92:95]
	v_mfma_f32_16x16x32_bf16 v[84:87], v[128:131], v[190:193], v[84:87]
	v_mfma_f32_16x16x32_bf16 v[76:79], v[136:139], v[190:193], v[76:79]
	v_mfma_f32_16x16x32_bf16 v[124:127], v[132:135], v[170:173], v[124:127]
	v_mfma_f32_16x16x32_bf16 v[120:123], v[140:143], v[170:173], v[120:123]
	v_mfma_f32_16x16x32_bf16 v[116:119], v[132:135], v[178:181], v[116:119]
	v_mfma_f32_16x16x32_bf16 v[108:111], v[140:143], v[178:181], v[108:111]
	v_mfma_f32_16x16x32_bf16 v[100:103], v[132:135], v[186:189], v[100:103]
	v_mfma_f32_16x16x32_bf16 v[92:95], v[140:143], v[186:189], v[92:95]
	v_mfma_f32_16x16x32_bf16 v[84:87], v[132:135], v[194:197], v[84:87]
	v_mfma_f32_16x16x32_bf16 v[76:79], v[140:143], v[194:197], v[76:79]
	s_barrier
	s_mov_b32 m0, s41
	v_lshl_add_u64 v[198:199], s[48:49], 0, v[200:201]
	ds_read_b128 v[210:213], v163 offset:0
	ds_read_b128 v[214:217], v163 offset:1024
	ds_read_b128 v[218:221], v163 offset:2048
	ds_read_b128 v[222:225], v163 offset:3072
	global_load_lds_dwordx4 v[198:199], off
	v_lshl_add_u64 v[226:227], s[48:49], 0, v[144:145]
	s_mov_b32 m0, s56
	s_nop 0
	global_load_lds_dwordx4 v[226:227], off
	s_barrier
	s_waitcnt lgkmcnt(0)
	v_mfma_f32_16x16x32_bf16 v[112:115], v[210:213], v[158:161], v[112:115]
	v_mfma_f32_16x16x32_bf16 v[104:107], v[218:221], v[158:161], v[104:107]
	v_mfma_f32_16x16x32_bf16 v[96:99], v[210:213], v[174:177], v[96:99]
	v_mfma_f32_16x16x32_bf16 v[88:91], v[218:221], v[174:177], v[88:91]
	v_mfma_f32_16x16x32_bf16 v[80:83], v[210:213], v[182:185], v[80:83]
	v_mfma_f32_16x16x32_bf16 v[72:75], v[218:221], v[182:185], v[72:75]
	v_mfma_f32_16x16x32_bf16 v[68:71], v[210:213], v[190:193], v[68:71]
	v_mfma_f32_16x16x32_bf16 v[64:67], v[218:221], v[190:193], v[64:67]
	v_mfma_f32_16x16x32_bf16 v[112:115], v[214:217], v[170:173], v[112:115]
	v_mfma_f32_16x16x32_bf16 v[104:107], v[222:225], v[170:173], v[104:107]
	v_mfma_f32_16x16x32_bf16 v[96:99], v[214:217], v[178:181], v[96:99]
	v_mfma_f32_16x16x32_bf16 v[88:91], v[222:225], v[178:181], v[88:91]
	v_mfma_f32_16x16x32_bf16 v[80:83], v[214:217], v[186:189], v[80:83]
	v_mfma_f32_16x16x32_bf16 v[72:75], v[222:225], v[186:189], v[72:75]
	v_mfma_f32_16x16x32_bf16 v[68:71], v[214:217], v[194:197], v[68:71]
	v_mfma_f32_16x16x32_bf16 v[64:67], v[222:225], v[194:197], v[64:67]
	s_mov_b32 m0, s53
	v_lshl_add_u64 v[230:231], s[50:51], 0, v[148:149]
	s_barrier
	ds_read_b128 v[158:161], v164 offset:0
	ds_read_b128 v[170:173], v164 offset:1024
	ds_read_b128 v[174:177], v164 offset:2048
	ds_read_b128 v[178:181], v164 offset:3072
	ds_read_b128 v[182:185], v164 offset:4096
	ds_read_b128 v[186:189], v164 offset:5120
	ds_read_b128 v[190:193], v164 offset:6144
	ds_read_b128 v[194:197], v164 offset:7168
	global_load_lds_dwordx4 v[230:231], off
	v_lshl_add_u64 v[232:233], s[50:51], 0, v[146:147]
	s_mov_b32 m0, s57
	s_nop 0
	global_load_lds_dwordx4 v[232:233], off
	s_barrier
	s_waitcnt lgkmcnt(0)
	v_mfma_f32_16x16x32_bf16 v[60:63], v[128:131], v[158:161], v[60:63]
	v_mfma_f32_16x16x32_bf16 v[56:59], v[136:139], v[158:161], v[56:59]
	v_mfma_f32_16x16x32_bf16 v[52:55], v[128:131], v[174:177], v[52:55]
	v_mfma_f32_16x16x32_bf16 v[44:47], v[136:139], v[174:177], v[44:47]
	v_mfma_f32_16x16x32_bf16 v[36:39], v[128:131], v[182:185], v[36:39]
	v_mfma_f32_16x16x32_bf16 v[28:31], v[136:139], v[182:185], v[28:31]
	v_mfma_f32_16x16x32_bf16 v[20:23], v[128:131], v[190:193], v[20:23]
	v_mfma_f32_16x16x32_bf16 v[12:15], v[136:139], v[190:193], v[12:15]
	v_mfma_f32_16x16x32_bf16 v[60:63], v[132:135], v[170:173], v[60:63]
	v_mfma_f32_16x16x32_bf16 v[56:59], v[140:143], v[170:173], v[56:59]
	v_mfma_f32_16x16x32_bf16 v[52:55], v[132:135], v[178:181], v[52:55]
	v_mfma_f32_16x16x32_bf16 v[44:47], v[140:143], v[178:181], v[44:47]
	v_mfma_f32_16x16x32_bf16 v[36:39], v[132:135], v[186:189], v[36:39]
	v_mfma_f32_16x16x32_bf16 v[28:31], v[140:143], v[186:189], v[28:31]
	v_mfma_f32_16x16x32_bf16 v[20:23], v[132:135], v[194:197], v[20:23]
	v_mfma_f32_16x16x32_bf16 v[12:15], v[140:143], v[194:197], v[12:15]
	s_barrier
	s_add_u32 s54, s48, 0x40000
	s_addc_u32 s55, s49, 0
	s_mov_b32 m0, s58
	v_lshl_add_u64 v[128:129], s[54:55], 0, v[200:201]
	global_load_lds_dwordx4 v[128:129], off
	v_lshl_add_u64 v[128:129], s[54:55], 0, v[144:145]
	s_mov_b32 m0, s59
	s_nop 0
	global_load_lds_dwordx4 v[128:129], off
	s_waitcnt vmcnt(6)
	s_barrier
	v_mfma_f32_16x16x32_bf16 v[48:51], v[210:213], v[158:161], v[48:51]
	v_mfma_f32_16x16x32_bf16 v[40:43], v[218:221], v[158:161], v[40:43]
	v_mfma_f32_16x16x32_bf16 v[32:35], v[210:213], v[174:177], v[32:35]
	v_mfma_f32_16x16x32_bf16 v[24:27], v[218:221], v[174:177], v[24:27]
	v_mfma_f32_16x16x32_bf16 v[16:19], v[210:213], v[182:185], v[16:19]
	v_mfma_f32_16x16x32_bf16 v[8:11], v[218:221], v[182:185], v[8:11]
	v_mfma_f32_16x16x32_bf16 v[4:7], v[210:213], v[190:193], v[4:7]
	v_mfma_f32_16x16x32_bf16 v[0:3], v[218:221], v[190:193], v[0:3]
	v_mfma_f32_16x16x32_bf16 v[48:51], v[214:217], v[170:173], v[48:51]
	v_mfma_f32_16x16x32_bf16 v[40:43], v[222:225], v[170:173], v[40:43]
	v_mfma_f32_16x16x32_bf16 v[32:35], v[214:217], v[178:181], v[32:35]
	v_mfma_f32_16x16x32_bf16 v[24:27], v[222:225], v[178:181], v[24:27]
	v_mfma_f32_16x16x32_bf16 v[16:19], v[214:217], v[186:189], v[16:19]
	v_mfma_f32_16x16x32_bf16 v[8:11], v[222:225], v[186:189], v[8:11]
	v_mfma_f32_16x16x32_bf16 v[4:7], v[214:217], v[194:197], v[4:7]
	v_mfma_f32_16x16x32_bf16 v[0:3], v[222:225], v[194:197], v[0:3]
	s_barrier
	ds_read_b128 v[128:131], v165 offset:0
	ds_read_b128 v[132:135], v165 offset:1024
	ds_read_b128 v[136:139], v165 offset:2048
	ds_read_b128 v[140:143], v165 offset:3072
	s_add_u32 s50, s50, 0x40000
	s_addc_u32 s51, s51, 0
	s_mov_b32 m0, s60
	v_lshl_add_u64 v[210:211], s[50:51], 0, v[148:149]
	ds_read_b128 v[158:161], v166 offset:0
	ds_read_b128 v[170:173], v166 offset:1024
	ds_read_b128 v[174:177], v166 offset:2048
	ds_read_b128 v[178:181], v166 offset:3072
	ds_read_b128 v[182:185], v166 offset:4096
	ds_read_b128 v[186:189], v166 offset:5120
	ds_read_b128 v[190:193], v166 offset:6144
	ds_read_b128 v[194:197], v166 offset:7168
	global_load_lds_dwordx4 v[210:211], off
	v_lshl_add_u64 v[210:211], s[50:51], 0, v[146:147]
	s_mov_b32 m0, s61
	s_nop 0
	global_load_lds_dwordx4 v[210:211], off
	s_waitcnt lgkmcnt(8)
	s_barrier
	s_waitcnt lgkmcnt(0)
	s_waitcnt lgkmcnt(0)
	v_mfma_f32_16x16x32_bf16 v[124:127], v[128:131], v[158:161], v[124:127]
	v_mfma_f32_16x16x32_bf16 v[120:123], v[136:139], v[158:161], v[120:123]
	v_mfma_f32_16x16x32_bf16 v[116:119], v[128:131], v[174:177], v[116:119]
	v_mfma_f32_16x16x32_bf16 v[108:111], v[136:139], v[174:177], v[108:111]
	v_mfma_f32_16x16x32_bf16 v[100:103], v[128:131], v[182:185], v[100:103]
	v_mfma_f32_16x16x32_bf16 v[92:95], v[136:139], v[182:185], v[92:95]
	v_mfma_f32_16x16x32_bf16 v[84:87], v[128:131], v[190:193], v[84:87]
	v_mfma_f32_16x16x32_bf16 v[76:79], v[136:139], v[190:193], v[76:79]
	v_mfma_f32_16x16x32_bf16 v[124:127], v[132:135], v[170:173], v[124:127]
	v_mfma_f32_16x16x32_bf16 v[120:123], v[140:143], v[170:173], v[120:123]
	v_mfma_f32_16x16x32_bf16 v[116:119], v[132:135], v[178:181], v[116:119]
	v_mfma_f32_16x16x32_bf16 v[108:111], v[140:143], v[178:181], v[108:111]
	v_mfma_f32_16x16x32_bf16 v[100:103], v[132:135], v[186:189], v[100:103]
	v_mfma_f32_16x16x32_bf16 v[92:95], v[140:143], v[186:189], v[92:95]
	v_mfma_f32_16x16x32_bf16 v[84:87], v[132:135], v[194:197], v[84:87]
	v_mfma_f32_16x16x32_bf16 v[76:79], v[140:143], v[194:197], v[76:79]
	s_barrier
	s_mov_b32 m0, s62
	v_lshl_add_u64 v[198:199], v[198:199], 0, s[34:35]
	ds_read_b128 v[210:213], v167 offset:0
	ds_read_b128 v[214:217], v167 offset:1024
	ds_read_b128 v[218:221], v167 offset:2048
	ds_read_b128 v[222:225], v167 offset:3072
	global_load_lds_dwordx4 v[198:199], off
	v_lshl_add_u64 v[198:199], v[226:227], 0, s[34:35]
	s_mov_b32 m0, s63
	s_nop 0
	global_load_lds_dwordx4 v[198:199], off
	s_barrier
	s_waitcnt lgkmcnt(0)
	v_mfma_f32_16x16x32_bf16 v[112:115], v[210:213], v[158:161], v[112:115]
	v_mfma_f32_16x16x32_bf16 v[104:107], v[218:221], v[158:161], v[104:107]
	v_mfma_f32_16x16x32_bf16 v[96:99], v[210:213], v[174:177], v[96:99]
	v_mfma_f32_16x16x32_bf16 v[88:91], v[218:221], v[174:177], v[88:91]
	v_mfma_f32_16x16x32_bf16 v[80:83], v[210:213], v[182:185], v[80:83]
	v_mfma_f32_16x16x32_bf16 v[72:75], v[218:221], v[182:185], v[72:75]
	v_mfma_f32_16x16x32_bf16 v[68:71], v[210:213], v[190:193], v[68:71]
	v_mfma_f32_16x16x32_bf16 v[64:67], v[218:221], v[190:193], v[64:67]
	v_mfma_f32_16x16x32_bf16 v[112:115], v[214:217], v[170:173], v[112:115]
	v_mfma_f32_16x16x32_bf16 v[104:107], v[222:225], v[170:173], v[104:107]
	v_mfma_f32_16x16x32_bf16 v[96:99], v[214:217], v[178:181], v[96:99]
	v_mfma_f32_16x16x32_bf16 v[88:91], v[222:225], v[178:181], v[88:91]
	v_mfma_f32_16x16x32_bf16 v[80:83], v[214:217], v[186:189], v[80:83]
	v_mfma_f32_16x16x32_bf16 v[72:75], v[222:225], v[186:189], v[72:75]
	v_mfma_f32_16x16x32_bf16 v[68:71], v[214:217], v[194:197], v[68:71]
	v_mfma_f32_16x16x32_bf16 v[64:67], v[222:225], v[194:197], v[64:67]
	s_mov_b32 m0, s64
	v_lshl_add_u64 v[198:199], v[230:231], 0, s[34:35]
	s_barrier
	ds_read_b128 v[158:161], v168 offset:0
	ds_read_b128 v[170:173], v168 offset:1024
	ds_read_b128 v[174:177], v168 offset:2048
	ds_read_b128 v[178:181], v168 offset:3072
	ds_read_b128 v[182:185], v168 offset:4096
	ds_read_b128 v[186:189], v168 offset:5120
	ds_read_b128 v[190:193], v168 offset:6144
	ds_read_b128 v[194:197], v168 offset:7168
	global_load_lds_dwordx4 v[198:199], off
	v_lshl_add_u64 v[198:199], v[232:233], 0, s[34:35]
	s_mov_b32 m0, s65
	s_nop 0
	global_load_lds_dwordx4 v[198:199], off
	s_barrier
	s_waitcnt lgkmcnt(0)
	v_mfma_f32_16x16x32_bf16 v[60:63], v[128:131], v[158:161], v[60:63]
	v_mfma_f32_16x16x32_bf16 v[56:59], v[136:139], v[158:161], v[56:59]
	v_mfma_f32_16x16x32_bf16 v[52:55], v[128:131], v[174:177], v[52:55]
	v_mfma_f32_16x16x32_bf16 v[44:47], v[136:139], v[174:177], v[44:47]
	v_mfma_f32_16x16x32_bf16 v[36:39], v[128:131], v[182:185], v[36:39]
	v_mfma_f32_16x16x32_bf16 v[28:31], v[136:139], v[182:185], v[28:31]
	v_mfma_f32_16x16x32_bf16 v[20:23], v[128:131], v[190:193], v[20:23]
	v_mfma_f32_16x16x32_bf16 v[12:15], v[136:139], v[190:193], v[12:15]
	v_mfma_f32_16x16x32_bf16 v[60:63], v[132:135], v[170:173], v[60:63]
	v_mfma_f32_16x16x32_bf16 v[56:59], v[140:143], v[170:173], v[56:59]
	v_mfma_f32_16x16x32_bf16 v[52:55], v[132:135], v[178:181], v[52:55]
	v_mfma_f32_16x16x32_bf16 v[44:47], v[140:143], v[178:181], v[44:47]
	v_mfma_f32_16x16x32_bf16 v[36:39], v[132:135], v[186:189], v[36:39]
	v_mfma_f32_16x16x32_bf16 v[28:31], v[140:143], v[186:189], v[28:31]
	v_mfma_f32_16x16x32_bf16 v[20:23], v[132:135], v[194:197], v[20:23]
	v_mfma_f32_16x16x32_bf16 v[12:15], v[140:143], v[194:197], v[12:15]
	s_barrier
	s_add_u32 s48, s48, 0x40080
	s_addc_u32 s49, s49, 0
	s_mov_b32 m0, s66
	v_lshl_add_u64 v[128:129], s[48:49], 0, v[200:201]
	global_load_lds_dwordx4 v[128:129], off
	v_lshl_add_u64 v[128:129], s[48:49], 0, v[144:145]
	s_mov_b32 m0, s67
	s_nop 0
	global_load_lds_dwordx4 v[128:129], off
	s_waitcnt vmcnt(6)
	s_barrier
	v_mfma_f32_16x16x32_bf16 v[48:51], v[210:213], v[158:161], v[48:51]
	v_mfma_f32_16x16x32_bf16 v[40:43], v[218:221], v[158:161], v[40:43]
	v_mfma_f32_16x16x32_bf16 v[32:35], v[210:213], v[174:177], v[32:35]
	v_mfma_f32_16x16x32_bf16 v[24:27], v[218:221], v[174:177], v[24:27]
	v_mfma_f32_16x16x32_bf16 v[16:19], v[210:213], v[182:185], v[16:19]
	v_mfma_f32_16x16x32_bf16 v[8:11], v[218:221], v[182:185], v[8:11]
	v_mfma_f32_16x16x32_bf16 v[4:7], v[210:213], v[190:193], v[4:7]
	v_mfma_f32_16x16x32_bf16 v[0:3], v[218:221], v[190:193], v[0:3]
	v_mfma_f32_16x16x32_bf16 v[48:51], v[214:217], v[170:173], v[48:51]
	v_mfma_f32_16x16x32_bf16 v[40:43], v[222:225], v[170:173], v[40:43]
	v_mfma_f32_16x16x32_bf16 v[32:35], v[214:217], v[178:181], v[32:35]
	v_mfma_f32_16x16x32_bf16 v[24:27], v[222:225], v[178:181], v[24:27]
	v_mfma_f32_16x16x32_bf16 v[16:19], v[214:217], v[186:189], v[16:19]
	v_mfma_f32_16x16x32_bf16 v[8:11], v[222:225], v[186:189], v[8:11]
	v_mfma_f32_16x16x32_bf16 v[4:7], v[214:217], v[194:197], v[4:7]
	v_mfma_f32_16x16x32_bf16 v[0:3], v[222:225], v[194:197], v[0:3]
	s_add_i32 vcc_lo, vcc_lo, 2
	s_add_u32 s46, s46, 0x100
	s_addc_u32 s47, s47, 0
	s_add_u32 s96, s96, 0x100
	s_addc_u32 s97, s97, 0
	s_cmp_gt_u32 vcc_lo, 13
	s_barrier
	s_cbranch_scc0 .LBB0_721
	s_min_i32 s3, s29, 6
	s_lshl_b32 s3, s3, 8
	v_or_b32_e32 v129, 0x700, v169
	v_add_u32_e32 v128, s3, v155
	v_add_u32_e32 v129, s3, v129
	v_lshl_or_b32 v160, s28, 8, v169
	v_lshl_add_u32 v128, v128, 2, v246
	v_lshl_add_u32 v129, v129, 2, v246
	ds_read_b32 v170, v128 offset:0
	ds_read_b32 v172, v128 offset:64
	ds_read_b32 v174, v128 offset:128
	ds_read_b32 v176, v128 offset:192
	ds_read_b32 v178, v128 offset:512
	ds_read_b32 v180, v128 offset:576
	ds_read_b32 v156, v128 offset:640
	ds_read_b32 v154, v128 offset:704
	ds_read_b128 v[140:143], v129 offset:0
	ds_read_b128 v[136:139], v129 offset:16
	ds_read_b128 v[132:135], v129 offset:512
	ds_read_b128 v[128:131], v129 offset:528
	v_lshl_add_u32 v171, s40, 8, v155
	v_ashrrev_i32_e32 v161, 31, v160
	v_mov_b64_e32 v[158:159], s[20:21]
	s_waitcnt lgkmcnt(0)
	v_mad_i64_i32 v[182:183], s[28:29], v171, s92, v[158:159]
	v_lshlrev_b64 v[160:161], 1, v[160:161]
	v_pk_fma_f32 v[126:127], v[126:127], v[170:171], v[142:143] op_sel_hi:[1,0,1]
	v_pk_fma_f32 v[124:125], v[124:125], v[170:171], v[140:141] op_sel_hi:[1,0,1]
	v_pk_fma_f32 v[184:185], v[122:123], v[170:171], v[138:139] op_sel_hi:[1,0,1]
	v_pk_fma_f32 v[122:123], v[120:121], v[170:171], v[136:137] op_sel_hi:[1,0,1]
	v_lshl_add_u64 v[182:183], v[182:183], 0, v[160:161]
	v_cvt_pk_bf16_f32 v120, v124, v125
	v_cvt_pk_bf16_f32 v121, v126, v127
	v_cvt_pk_bf16_f32 v122, v122, v123
	v_cvt_pk_bf16_f32 v123, v184, v185
	global_store_dwordx4 v[182:183], v[120:123], off
	v_pk_fma_f32 v[114:115], v[114:115], v[170:171], v[134:135] op_sel_hi:[1,0,1]
	v_pk_fma_f32 v[112:113], v[112:113], v[170:171], v[132:133] op_sel_hi:[1,0,1]
	v_pk_fma_f32 v[120:121], v[106:107], v[170:171], v[130:131] op_sel_hi:[1,0,1]
	v_pk_fma_f32 v[106:107], v[104:105], v[170:171], v[128:129] op_sel_hi:[1,0,1]
	v_cvt_pk_bf16_f32 v104, v112, v113
	v_cvt_pk_bf16_f32 v105, v114, v115
	v_cvt_pk_bf16_f32 v106, v106, v107
	v_cvt_pk_bf16_f32 v107, v120, v121
	global_store_dwordx4 v[182:183], v[104:107], off offset:256
	v_pk_fma_f32 v[110:111], v[110:111], v[172:173], v[138:139] op_sel_hi:[1,0,1]
	v_pk_fma_f32 v[108:109], v[108:109], v[172:173], v[136:137] op_sel_hi:[1,0,1]
	v_or_b32_e32 v104, 16, v171
	v_mad_i64_i32 v[104:105], s[28:29], v104, s92, v[158:159]
	v_lshl_add_u64 v[112:113], v[104:105], 0, v[160:161]
	v_pk_fma_f32 v[106:107], v[118:119], v[172:173], v[142:143] op_sel_hi:[1,0,1]
	v_pk_fma_f32 v[104:105], v[116:117], v[172:173], v[140:141] op_sel_hi:[1,0,1]
	v_pk_fma_f32 v[98:99], v[98:99], v[172:173], v[134:135] op_sel_hi:[1,0,1]
	v_cvt_pk_bf16_f32 v104, v104, v105
	v_cvt_pk_bf16_f32 v105, v106, v107
	v_cvt_pk_bf16_f32 v106, v108, v109
	v_cvt_pk_bf16_f32 v107, v110, v111
	global_store_dwordx4 v[112:113], v[104:107], off
	v_pk_fma_f32 v[96:97], v[96:97], v[172:173], v[132:133] op_sel_hi:[1,0,1]
	v_pk_fma_f32 v[94:95], v[94:95], v[174:175], v[138:139] op_sel_hi:[1,0,1]
	v_pk_fma_f32 v[104:105], v[90:91], v[172:173], v[130:131] op_sel_hi:[1,0,1]
	v_pk_fma_f32 v[90:91], v[88:89], v[172:173], v[128:129] op_sel_hi:[1,0,1]
	v_cvt_pk_bf16_f32 v88, v96, v97
	v_cvt_pk_bf16_f32 v89, v98, v99
	v_cvt_pk_bf16_f32 v90, v90, v91
	v_cvt_pk_bf16_f32 v91, v104, v105
	global_store_dwordx4 v[112:113], v[88:91], off offset:256
	v_pk_fma_f32 v[92:93], v[92:93], v[174:175], v[136:137] op_sel_hi:[1,0,1]
	v_pk_fma_f32 v[82:83], v[82:83], v[174:175], v[134:135] op_sel_hi:[1,0,1]
	v_or_b32_e32 v88, 32, v171
	v_mad_i64_i32 v[88:89], s[28:29], v88, s92, v[158:159]
	v_lshl_add_u64 v[96:97], v[88:89], 0, v[160:161]
	v_pk_fma_f32 v[90:91], v[102:103], v[174:175], v[142:143] op_sel_hi:[1,0,1]
	v_pk_fma_f32 v[88:89], v[100:101], v[174:175], v[140:141] op_sel_hi:[1,0,1]
	v_pk_fma_f32 v[80:81], v[80:81], v[174:175], v[132:133] op_sel_hi:[1,0,1]
	v_cvt_pk_bf16_f32 v88, v88, v89
	v_cvt_pk_bf16_f32 v89, v90, v91
	v_cvt_pk_bf16_f32 v90, v92, v93
	v_cvt_pk_bf16_f32 v91, v94, v95
	global_store_dwordx4 v[96:97], v[88:91], off
	v_pk_fma_f32 v[78:79], v[78:79], v[176:177], v[138:139] op_sel_hi:[1,0,1]
	v_pk_fma_f32 v[76:77], v[76:77], v[176:177], v[136:137] op_sel_hi:[1,0,1]
	v_pk_fma_f32 v[88:89], v[74:75], v[174:175], v[130:131] op_sel_hi:[1,0,1]
	v_pk_fma_f32 v[74:75], v[72:73], v[174:175], v[128:129] op_sel_hi:[1,0,1]
	v_cvt_pk_bf16_f32 v72, v80, v81
	v_cvt_pk_bf16_f32 v73, v82, v83
	v_cvt_pk_bf16_f32 v74, v74, v75
	v_cvt_pk_bf16_f32 v75, v88, v89
	global_store_dwordx4 v[96:97], v[72:75], off offset:256
	v_pk_fma_f32 v[70:71], v[70:71], v[176:177], v[134:135] op_sel_hi:[1,0,1]
	v_pk_fma_f32 v[68:69], v[68:69], v[176:177], v[132:133] op_sel_hi:[1,0,1]
	v_or_b32_e32 v72, 48, v171
	v_mad_i64_i32 v[72:73], s[28:29], v72, s92, v[158:159]
	v_lshl_add_u64 v[80:81], v[72:73], 0, v[160:161]
	v_pk_fma_f32 v[74:75], v[86:87], v[176:177], v[142:143] op_sel_hi:[1,0,1]
	v_pk_fma_f32 v[72:73], v[84:85], v[176:177], v[140:141] op_sel_hi:[1,0,1]
	v_pk_fma_f32 v[62:63], v[62:63], v[178:179], v[142:143] op_sel_hi:[1,0,1]
	v_cvt_pk_bf16_f32 v72, v72, v73
	v_cvt_pk_bf16_f32 v73, v74, v75
	v_cvt_pk_bf16_f32 v74, v76, v77
	v_cvt_pk_bf16_f32 v75, v78, v79
	global_store_dwordx4 v[80:81], v[72:75], off
	v_pk_fma_f32 v[60:61], v[60:61], v[178:179], v[140:141] op_sel_hi:[1,0,1]
	v_pk_fma_f32 v[50:51], v[50:51], v[178:179], v[134:135] op_sel_hi:[1,0,1]
	v_pk_fma_f32 v[72:73], v[66:67], v[176:177], v[130:131] op_sel_hi:[1,0,1]
	v_pk_fma_f32 v[66:67], v[64:65], v[176:177], v[128:129] op_sel_hi:[1,0,1]
	v_cvt_pk_bf16_f32 v64, v68, v69
	v_cvt_pk_bf16_f32 v65, v70, v71
	v_cvt_pk_bf16_f32 v66, v66, v67
	v_cvt_pk_bf16_f32 v67, v72, v73
	global_store_dwordx4 v[80:81], v[64:67], off offset:256
	v_pk_fma_f32 v[48:49], v[48:49], v[178:179], v[132:133] op_sel_hi:[1,0,1]
	v_pk_fma_f32 v[46:47], v[46:47], v[180:181], v[138:139] op_sel_hi:[1,0,1]
	v_add_u32_e32 v64, 0x80, v171
	v_mad_i64_i32 v[64:65], s[28:29], v64, s92, v[158:159]
	v_pk_fma_f32 v[66:67], v[58:59], v[178:179], v[138:139] op_sel_hi:[1,0,1]
	v_pk_fma_f32 v[58:59], v[56:57], v[178:179], v[136:137] op_sel_hi:[1,0,1]
	v_lshl_add_u64 v[64:65], v[64:65], 0, v[160:161]
	v_cvt_pk_bf16_f32 v56, v60, v61
	v_cvt_pk_bf16_f32 v57, v62, v63
	v_cvt_pk_bf16_f32 v58, v58, v59
	v_cvt_pk_bf16_f32 v59, v66, v67
	global_store_dwordx4 v[64:65], v[56:59], off
	v_pk_fma_f32 v[44:45], v[44:45], v[180:181], v[136:137] op_sel_hi:[1,0,1]
	v_pk_fma_f32 v[34:35], v[34:35], v[180:181], v[134:135] op_sel_hi:[1,0,1]
	v_pk_fma_f32 v[56:57], v[42:43], v[178:179], v[130:131] op_sel_hi:[1,0,1]
	v_pk_fma_f32 v[42:43], v[40:41], v[178:179], v[128:129] op_sel_hi:[1,0,1]
	v_cvt_pk_bf16_f32 v40, v48, v49
	v_cvt_pk_bf16_f32 v41, v50, v51
	v_cvt_pk_bf16_f32 v42, v42, v43
	v_cvt_pk_bf16_f32 v43, v56, v57
	global_store_dwordx4 v[64:65], v[40:43], off offset:256
	v_pk_fma_f32 v[32:33], v[32:33], v[180:181], v[132:133] op_sel_hi:[1,0,1]
	v_pk_fma_f32 v[30:31], v[30:31], v[156:157], v[138:139] op_sel_hi:[1,0,1]
	v_add_u32_e32 v40, 0x90, v171
	v_mad_i64_i32 v[40:41], s[28:29], v40, s92, v[158:159]
	v_lshl_add_u64 v[48:49], v[40:41], 0, v[160:161]
	v_pk_fma_f32 v[42:43], v[54:55], v[180:181], v[142:143] op_sel_hi:[1,0,1]
	v_pk_fma_f32 v[40:41], v[52:53], v[180:181], v[140:141] op_sel_hi:[1,0,1]
	v_pk_fma_f32 v[28:29], v[28:29], v[156:157], v[136:137] op_sel_hi:[1,0,1]
	v_cvt_pk_bf16_f32 v40, v40, v41
	v_cvt_pk_bf16_f32 v41, v42, v43
	v_cvt_pk_bf16_f32 v42, v44, v45
	v_cvt_pk_bf16_f32 v43, v46, v47
	global_store_dwordx4 v[48:49], v[40:43], off
	v_pk_fma_f32 v[18:19], v[18:19], v[156:157], v[134:135] op_sel_hi:[1,0,1]
	v_pk_fma_f32 v[16:17], v[16:17], v[156:157], v[132:133] op_sel_hi:[1,0,1]
	v_pk_fma_f32 v[40:41], v[26:27], v[180:181], v[130:131] op_sel_hi:[1,0,1]
	v_pk_fma_f32 v[26:27], v[24:25], v[180:181], v[128:129] op_sel_hi:[1,0,1]
	v_cvt_pk_bf16_f32 v24, v32, v33
	v_cvt_pk_bf16_f32 v25, v34, v35
	v_cvt_pk_bf16_f32 v26, v26, v27
	v_cvt_pk_bf16_f32 v27, v40, v41
	global_store_dwordx4 v[48:49], v[24:27], off offset:256
	v_pk_fma_f32 v[14:15], v[14:15], v[154:155], v[138:139] op_sel_hi:[1,0,1]
	v_pk_fma_f32 v[12:13], v[12:13], v[154:155], v[136:137] op_sel_hi:[1,0,1]
	v_add_u32_e32 v24, 0xa0, v171
	v_mad_i64_i32 v[24:25], s[28:29], v24, s92, v[158:159]
	v_lshl_add_u64 v[32:33], v[24:25], 0, v[160:161]
	v_pk_fma_f32 v[26:27], v[38:39], v[156:157], v[142:143] op_sel_hi:[1,0,1]
	v_pk_fma_f32 v[24:25], v[36:37], v[156:157], v[140:141] op_sel_hi:[1,0,1]
	v_pk_fma_f32 v[6:7], v[6:7], v[154:155], v[134:135] op_sel_hi:[1,0,1]
	v_cvt_pk_bf16_f32 v24, v24, v25
	v_cvt_pk_bf16_f32 v25, v26, v27
	v_cvt_pk_bf16_f32 v26, v28, v29
	v_cvt_pk_bf16_f32 v27, v30, v31
	global_store_dwordx4 v[32:33], v[24:27], off
	v_pk_fma_f32 v[4:5], v[4:5], v[154:155], v[132:133] op_sel_hi:[1,0,1]
	s_and_b64 vcc, exec, s[36:37]
	v_pk_fma_f32 v[24:25], v[10:11], v[156:157], v[130:131] op_sel_hi:[1,0,1]
	v_pk_fma_f32 v[10:11], v[8:9], v[156:157], v[128:129] op_sel_hi:[1,0,1]
	v_cvt_pk_bf16_f32 v8, v16, v17
	v_cvt_pk_bf16_f32 v9, v18, v19
	v_cvt_pk_bf16_f32 v10, v10, v11
	v_cvt_pk_bf16_f32 v11, v24, v25
	global_store_dwordx4 v[32:33], v[8:11], off offset:256
	s_mov_b32 s40, s38
	s_mov_b64 s[48:49], s[44:45]
	v_add_u32_e32 v8, 0xb0, v171
	v_mad_i64_i32 v[8:9], s[28:29], v8, s92, v[158:159]
	v_lshl_add_u64 v[16:17], v[8:9], 0, v[160:161]
	v_pk_fma_f32 v[10:11], v[22:23], v[154:155], v[142:143] op_sel_hi:[1,0,1]
	v_pk_fma_f32 v[8:9], v[20:21], v[154:155], v[140:141] op_sel_hi:[1,0,1]
	s_mov_b32 s28, s2
	v_cvt_pk_bf16_f32 v8, v8, v9
	v_cvt_pk_bf16_f32 v9, v10, v11
	v_cvt_pk_bf16_f32 v10, v12, v13
	v_cvt_pk_bf16_f32 v11, v14, v15
	global_store_dwordx4 v[16:17], v[8:11], off
	s_mov_b32 s29, s72
	s_mov_b64 s[46:47], s[42:43]
	v_pk_fma_f32 v[8:9], v[2:3], v[154:155], v[130:131] op_sel_hi:[1,0,1]
	v_pk_fma_f32 v[2:3], v[0:1], v[154:155], v[128:129] op_sel_hi:[1,0,1]
	v_cvt_pk_bf16_f32 v0, v4, v5
	v_cvt_pk_bf16_f32 v1, v6, v7
	v_cvt_pk_bf16_f32 v2, v2, v3
	v_cvt_pk_bf16_f32 v3, v8, v9
	global_store_dwordx4 v[16:17], v[0:3], off offset:256
	s_cbranch_vccz .LBB0_718
	s_waitcnt vmcnt(0)
	s_cmpk_gt_u32 s52, 0xff
	s_cbranch_scc1 .LBB0_725
	s_barrier
